# L1 invalidate by wave 1 at arrival + flat barrier + write-through residual-output stores
# speedup vs baseline: 1.0024x; 1.0024x over previous
; DI unsigned xb_add(unsigned* q, unsigned v) { return __hip_atomic_fetch_add(q, v, __ATOMIC_RELAXED, __HIP_MEMORY_SCOPE_AGENT); }
; DI void grid_bar(unsigned* bar, volatile LAS unsigned* st, int wid) {
;     ...
;             const unsigned old = xb_add(&bar[XB_XSUB(x)], 1u);
;             const unsigned gen = old / nloc;
;             if (old + 1u == (gen + 1u) * nloc) {
.LBB0_261:
	s_or_b64 exec, exec, s[14:15]
	v_cvt_f32_u32_e32 v4, v2
	s_waitcnt vmcnt(0)
	v_readfirstlane_b32 s12, v3
	v_sub_u32_e32 v3, 0, v2
	v_rcp_iflag_f32_e32 v4, v4
	v_add_u32_e32 v5, s12, v1
	v_mul_f32_e32 v4, 0x4f7ffffe, v4
	v_cvt_u32_f32_e32 v4, v4
	v_mul_lo_u32 v1, v3, v4
	v_mul_hi_u32 v1, v4, v1
	v_add_u32_e32 v1, v4, v1
	v_mul_hi_u32 v1, v5, v1
	v_mul_lo_u32 v3, v1, v2
	v_sub_u32_e32 v3, v5, v3
	v_add_u32_e32 v4, 1, v1
	v_cmp_ge_u32_e32 vcc, v3, v2
	s_nop 1
	v_cndmask_b32_e32 v1, v1, v4, vcc
	v_sub_u32_e32 v4, v3, v2
	v_cndmask_b32_e32 v3, v3, v4, vcc
	v_add_u32_e32 v4, 1, v1
	v_cmp_ge_u32_e32 vcc, v3, v2
	v_add_u32_e32 v3, 1, v5
	s_nop 0
	v_cndmask_b32_e32 v1, v1, v4, vcc
	v_mul_lo_u32 v4, v2, v1
	v_add_u32_e32 v2, v4, v2
	v_cmp_ne_u32_e32 vcc, v3, v2
	s_and_saveexec_b64 s[12:13], vcc
	s_xor_b64 s[12:13], exec, s[12:13]
	s_cbranch_execz .LBB0_275
	s_waitcnt lgkmcnt(0)
	v_add_u32_e32 v4, 1, v1
	v_mul_lo_u32 v4, v4, v0
	v_mov_b32_e32 v2, 0xcd83000
	s_mov_b32 s28, 0
